# P6 MIXB and P9 MB output stores sc1 (write-through), on top of v089
# baseline (speedup 1.0000x reference)
.LBB0_729:
	v_mul_f32_e32 v157, v125, v125
	v_mul_f32_e32 v160, v127, v127
	v_fmac_f32_e32 v157, v124, v124
	v_fmac_f32_e32 v160, v126, v126
	v_add_f32_e32 v157, v157, v160
	v_mul_f32_e32 v160, v121, v121
	v_fmac_f32_e32 v160, v120, v120
	v_cvt_pk_bf16_f32 v124, v124, v125
	v_cvt_pk_bf16_f32 v125, v126, v127
	v_cvt_pk_bf16_f32 v126, v120, v121
	v_mul_f32_e32 v120, v117, v117
	v_mul_f32_e32 v121, v119, v119
	v_fmac_f32_e32 v120, v116, v116
	v_fmac_f32_e32 v121, v118, v118
	v_add_f32_e32 v120, v120, v121
	v_mul_f32_e32 v121, v113, v113
	v_and_b32_e32 v155, 64, v154
	v_fmac_f32_e32 v121, v112, v112
	v_xor_b32_e32 v147, 16, v154
	v_add_u32_e32 v155, 64, v155
	v_add_f32_e32 v157, v157, v160
	v_mul_f32_e32 v160, v123, v123
	v_add_f32_e32 v120, v120, v121
	v_mul_f32_e32 v121, v115, v115
	v_cmp_lt_i32_e32 vcc, v147, v155
	v_fmac_f32_e32 v160, v122, v122
	v_fmac_f32_e32 v121, v114, v114
	v_cndmask_b32_e32 v147, v154, v147, vcc
	v_add_f32_e32 v157, v160, v157
	v_add_f32_e32 v120, v121, v120
	v_lshlrev_b32_e32 v156, 2, v147
	v_xor_b32_e32 v147, 32, v154
	v_cvt_pk_bf16_f32 v127, v122, v123
	v_add_f32_e32 v122, v157, v120
	v_cmp_lt_i32_e32 vcc, v147, v155
	ds_bpermute_b32 v123, v156, v122
	v_lshl_add_u32 v146, s28, 8, v148
	v_cndmask_b32_e32 v147, v154, v147, vcc
	v_lshlrev_b32_e32 v155, 2, v147
	v_ashrrev_i32_e32 v147, 31, v146
	v_lshl_or_b32 v144, s12, 8, v150
	v_lshlrev_b64 v[158:159], 11, v[146:147]
	v_ashrrev_i32_e32 v145, 31, v144
	v_lshl_add_u64 v[120:121], s[8:9], 0, v[158:159]
	v_lshl_add_u64 v[158:159], v[144:145], 1, v[120:121]
	v_cvt_pk_bf16_f32 v120, v116, v117
	s_waitcnt lgkmcnt(0)
	v_add_f32_e32 v116, v122, v123
	ds_bpermute_b32 v117, v155, v116
	s_lshl_b32 s28, s12, 2
	s_ashr_i32 s29, s28, 31
	v_cvt_pk_bf16_f32 v121, v118, v119
	v_cvt_pk_bf16_f32 v122, v112, v113
	v_cvt_pk_bf16_f32 v123, v114, v115
	global_store_dwordx4 v[158:159], v[124:127], off sc1
	global_store_dwordx4 v[158:159], v[120:123], off offset:256 sc1
	s_and_saveexec_b64 s[30:31], s[4:5]
	s_cbranch_execz .LBB0_731
	v_lshlrev_b64 v[112:113], 6, v[146:147]
	v_lshl_add_u64 v[112:113], s[10:11], 0, v[112:113]
	v_lshl_add_u64 v[112:113], s[28:29], 2, v[112:113]
	s_lshl_b32 s12, s43, 2
	s_waitcnt lgkmcnt(0)
	v_add_f32_e32 v114, v116, v117
	v_lshl_add_u64 v[112:113], v[112:113], 0, s[12:13]
	global_store_dword v[112:113], v114, off
.LBB0_731:
	s_or_b64 exec, exec, s[30:31]
	v_mul_f32_e32 v116, v109, v109
	s_waitcnt lgkmcnt(0)
	v_mul_f32_e32 v117, v111, v111
	v_fmac_f32_e32 v116, v108, v108
	v_fmac_f32_e32 v117, v110, v110
	v_add_f32_e32 v116, v116, v117
	v_mul_f32_e32 v117, v105, v105
	v_fmac_f32_e32 v117, v104, v104
	v_cvt_pk_bf16_f32 v108, v108, v109
	v_cvt_pk_bf16_f32 v109, v110, v111
	v_cvt_pk_bf16_f32 v110, v104, v105
	v_mul_f32_e32 v104, v101, v101
	v_mul_f32_e32 v105, v103, v103
	v_fmac_f32_e32 v104, v100, v100
	v_fmac_f32_e32 v105, v102, v102
	v_add_f32_e32 v104, v104, v105
	v_mul_f32_e32 v105, v97, v97
	v_fmac_f32_e32 v105, v96, v96
	v_add_f32_e32 v116, v116, v117
	v_mul_f32_e32 v117, v107, v107
	v_add_f32_e32 v104, v104, v105
	v_mul_f32_e32 v105, v99, v99
	v_fmac_f32_e32 v117, v106, v106
	v_fmac_f32_e32 v105, v98, v98
	v_add_f32_e32 v116, v117, v116
	v_add_f32_e32 v104, v105, v104
	v_cvt_pk_bf16_f32 v111, v106, v107
	v_add_f32_e32 v106, v116, v104
	ds_bpermute_b32 v107, v156, v106
	v_or_b32_e32 v112, 16, v146
	v_ashrrev_i32_e32 v113, 31, v112
	v_lshlrev_b64 v[114:115], 11, v[112:113]
	v_lshl_add_u64 v[104:105], s[8:9], 0, v[114:115]
	v_lshl_add_u64 v[114:115], v[144:145], 1, v[104:105]
	v_cvt_pk_bf16_f32 v104, v100, v101
	s_waitcnt lgkmcnt(0)
	v_add_f32_e32 v100, v106, v107
	ds_bpermute_b32 v101, v155, v100
	v_cvt_pk_bf16_f32 v105, v102, v103
	v_cvt_pk_bf16_f32 v106, v96, v97
	v_cvt_pk_bf16_f32 v107, v98, v99
	global_store_dwordx4 v[114:115], v[108:111], off sc1
	global_store_dwordx4 v[114:115], v[104:107], off offset:256 sc1
	s_and_saveexec_b64 s[30:31], s[4:5]
	s_cbranch_execz .LBB0_733
	v_lshlrev_b64 v[96:97], 6, v[112:113]
	v_lshl_add_u64 v[96:97], s[10:11], 0, v[96:97]
	v_lshl_add_u64 v[96:97], s[28:29], 2, v[96:97]
	s_lshl_b32 s12, s43, 2
	s_waitcnt lgkmcnt(0)
	v_add_f32_e32 v98, v100, v101
	v_lshl_add_u64 v[96:97], v[96:97], 0, s[12:13]
	global_store_dword v[96:97], v98, off
.LBB0_733:
	s_or_b64 exec, exec, s[30:31]
	v_mul_f32_e32 v100, v93, v93
	s_waitcnt lgkmcnt(0)
	v_mul_f32_e32 v101, v95, v95
	v_fmac_f32_e32 v100, v92, v92
	v_fmac_f32_e32 v101, v94, v94
	v_add_f32_e32 v100, v100, v101
	v_mul_f32_e32 v101, v89, v89
	v_fmac_f32_e32 v101, v88, v88
	v_cvt_pk_bf16_f32 v92, v92, v93
	v_cvt_pk_bf16_f32 v93, v94, v95
	v_cvt_pk_bf16_f32 v94, v88, v89
	v_mul_f32_e32 v88, v85, v85
	v_mul_f32_e32 v89, v87, v87
	v_fmac_f32_e32 v88, v84, v84
	v_fmac_f32_e32 v89, v86, v86
	v_add_f32_e32 v88, v88, v89
	v_mul_f32_e32 v89, v81, v81
	v_fmac_f32_e32 v89, v80, v80
	v_add_f32_e32 v100, v100, v101
	v_mul_f32_e32 v101, v91, v91
	v_add_f32_e32 v88, v88, v89
	v_mul_f32_e32 v89, v83, v83
	v_fmac_f32_e32 v101, v90, v90
	v_fmac_f32_e32 v89, v82, v82
	v_add_f32_e32 v100, v101, v100
	v_add_f32_e32 v88, v89, v88
	v_cvt_pk_bf16_f32 v95, v90, v91
	v_add_f32_e32 v90, v100, v88
	ds_bpermute_b32 v91, v156, v90
	v_or_b32_e32 v96, 32, v146
	v_ashrrev_i32_e32 v97, 31, v96
	v_lshlrev_b64 v[98:99], 11, v[96:97]
	v_lshl_add_u64 v[88:89], s[8:9], 0, v[98:99]
	v_lshl_add_u64 v[98:99], v[144:145], 1, v[88:89]
	v_cvt_pk_bf16_f32 v88, v84, v85
	s_waitcnt lgkmcnt(0)
	v_add_f32_e32 v84, v90, v91
	ds_bpermute_b32 v85, v155, v84
	v_cvt_pk_bf16_f32 v89, v86, v87
	v_cvt_pk_bf16_f32 v90, v80, v81
	v_cvt_pk_bf16_f32 v91, v82, v83
	global_store_dwordx4 v[98:99], v[92:95], off sc1
	global_store_dwordx4 v[98:99], v[88:91], off offset:256 sc1
	s_and_saveexec_b64 s[30:31], s[4:5]
	s_cbranch_execz .LBB0_735
	v_lshlrev_b64 v[80:81], 6, v[96:97]
	v_lshl_add_u64 v[80:81], s[10:11], 0, v[80:81]
	v_lshl_add_u64 v[80:81], s[28:29], 2, v[80:81]
	s_lshl_b32 s12, s43, 2
	s_waitcnt lgkmcnt(0)
	v_add_f32_e32 v82, v84, v85
	v_lshl_add_u64 v[80:81], v[80:81], 0, s[12:13]
	global_store_dword v[80:81], v82, off
.LBB0_735:
	s_or_b64 exec, exec, s[30:31]
	v_mul_f32_e32 v84, v77, v77
	s_waitcnt lgkmcnt(0)
	v_mul_f32_e32 v85, v79, v79
	v_fmac_f32_e32 v84, v76, v76
	v_fmac_f32_e32 v85, v78, v78
	v_add_f32_e32 v84, v84, v85
	v_mul_f32_e32 v85, v73, v73
	v_fmac_f32_e32 v85, v72, v72
	v_cvt_pk_bf16_f32 v76, v76, v77
	v_cvt_pk_bf16_f32 v77, v78, v79
	v_cvt_pk_bf16_f32 v78, v72, v73
	v_mul_f32_e32 v72, v69, v69
	v_mul_f32_e32 v73, v71, v71
	v_fmac_f32_e32 v72, v68, v68
	v_fmac_f32_e32 v73, v70, v70
	v_add_f32_e32 v72, v72, v73
	v_mul_f32_e32 v73, v65, v65
	v_fmac_f32_e32 v73, v64, v64
	v_add_f32_e32 v84, v84, v85
	v_mul_f32_e32 v85, v75, v75
	v_add_f32_e32 v72, v72, v73
	v_mul_f32_e32 v73, v67, v67
	v_fmac_f32_e32 v85, v74, v74
	v_fmac_f32_e32 v73, v66, v66
	v_add_f32_e32 v84, v85, v84
	v_add_f32_e32 v72, v73, v72
	v_cvt_pk_bf16_f32 v79, v74, v75
	v_add_f32_e32 v74, v84, v72
	ds_bpermute_b32 v75, v156, v74
	v_or_b32_e32 v80, 48, v146
	v_ashrrev_i32_e32 v81, 31, v80
	v_lshlrev_b64 v[82:83], 11, v[80:81]
	v_lshl_add_u64 v[72:73], s[8:9], 0, v[82:83]
	v_lshl_add_u64 v[82:83], v[144:145], 1, v[72:73]
	v_cvt_pk_bf16_f32 v72, v68, v69
	s_waitcnt lgkmcnt(0)
	v_add_f32_e32 v68, v74, v75
	ds_bpermute_b32 v69, v155, v68
	v_cvt_pk_bf16_f32 v73, v70, v71
	v_cvt_pk_bf16_f32 v74, v64, v65
	v_cvt_pk_bf16_f32 v75, v66, v67
	global_store_dwordx4 v[82:83], v[76:79], off sc1
	global_store_dwordx4 v[82:83], v[72:75], off offset:256 sc1
	s_and_saveexec_b64 s[30:31], s[4:5]
	s_cbranch_execz .LBB0_737
	v_lshlrev_b64 v[64:65], 6, v[80:81]
	v_lshl_add_u64 v[64:65], s[10:11], 0, v[64:65]
	v_lshl_add_u64 v[64:65], s[28:29], 2, v[64:65]
	s_lshl_b32 s12, s43, 2
	s_waitcnt lgkmcnt(0)
	v_add_f32_e32 v66, v68, v69
	v_lshl_add_u64 v[64:65], v[64:65], 0, s[12:13]
	global_store_dword v[64:65], v66, off
.LBB0_737:
	s_or_b64 exec, exec, s[30:31]
	v_mul_f32_e32 v68, v61, v61
	s_waitcnt lgkmcnt(0)
	v_mul_f32_e32 v69, v63, v63
	v_fmac_f32_e32 v68, v60, v60
	v_fmac_f32_e32 v69, v62, v62
	v_add_f32_e32 v68, v68, v69
	v_mul_f32_e32 v69, v57, v57
	v_fmac_f32_e32 v69, v56, v56
	v_cvt_pk_bf16_f32 v60, v60, v61
	v_cvt_pk_bf16_f32 v61, v62, v63
	v_cvt_pk_bf16_f32 v62, v56, v57
	v_mul_f32_e32 v56, v53, v53
	v_mul_f32_e32 v57, v55, v55
	v_fmac_f32_e32 v56, v52, v52
	v_fmac_f32_e32 v57, v54, v54
	v_add_f32_e32 v56, v56, v57
	v_mul_f32_e32 v57, v49, v49
	v_fmac_f32_e32 v57, v48, v48
	v_add_f32_e32 v68, v68, v69
	v_mul_f32_e32 v69, v59, v59
	v_add_f32_e32 v56, v56, v57
	v_mul_f32_e32 v57, v51, v51
	v_fmac_f32_e32 v69, v58, v58
	v_fmac_f32_e32 v57, v50, v50
	v_add_f32_e32 v68, v69, v68
	v_add_f32_e32 v56, v57, v56
	v_cvt_pk_bf16_f32 v63, v58, v59
	v_add_f32_e32 v58, v68, v56
	ds_bpermute_b32 v59, v156, v58
	v_add_u32_e32 v64, 0x80, v146
	v_ashrrev_i32_e32 v65, 31, v64
	v_lshlrev_b64 v[66:67], 11, v[64:65]
	v_lshl_add_u64 v[56:57], s[8:9], 0, v[66:67]
	v_lshl_add_u64 v[66:67], v[144:145], 1, v[56:57]
	v_cvt_pk_bf16_f32 v56, v52, v53
	s_waitcnt lgkmcnt(0)
	v_add_f32_e32 v52, v58, v59
	ds_bpermute_b32 v53, v155, v52
	v_cvt_pk_bf16_f32 v57, v54, v55
	v_cvt_pk_bf16_f32 v58, v48, v49
	v_cvt_pk_bf16_f32 v59, v50, v51
	global_store_dwordx4 v[66:67], v[60:63], off sc1
	global_store_dwordx4 v[66:67], v[56:59], off offset:256 sc1
	s_and_saveexec_b64 s[30:31], s[4:5]
	s_cbranch_execz .LBB0_739
	v_lshlrev_b64 v[48:49], 6, v[64:65]
	v_lshl_add_u64 v[48:49], s[10:11], 0, v[48:49]
	v_lshl_add_u64 v[48:49], s[28:29], 2, v[48:49]
	s_lshl_b32 s12, s43, 2
	s_waitcnt lgkmcnt(0)
	v_add_f32_e32 v50, v52, v53
	v_lshl_add_u64 v[48:49], v[48:49], 0, s[12:13]
	global_store_dword v[48:49], v50, off
.LBB0_739:
	s_or_b64 exec, exec, s[30:31]
	v_mul_f32_e32 v52, v45, v45
	s_waitcnt lgkmcnt(0)
	v_mul_f32_e32 v53, v47, v47
	v_fmac_f32_e32 v52, v44, v44
	v_fmac_f32_e32 v53, v46, v46
	v_add_f32_e32 v52, v52, v53
	v_mul_f32_e32 v53, v41, v41
	v_fmac_f32_e32 v53, v40, v40
	v_cvt_pk_bf16_f32 v44, v44, v45
	v_cvt_pk_bf16_f32 v45, v46, v47
	v_cvt_pk_bf16_f32 v46, v40, v41
	v_mul_f32_e32 v40, v37, v37
	v_mul_f32_e32 v41, v39, v39
	v_fmac_f32_e32 v40, v36, v36
	v_fmac_f32_e32 v41, v38, v38
	v_add_f32_e32 v40, v40, v41
	v_mul_f32_e32 v41, v33, v33
	v_fmac_f32_e32 v41, v32, v32
	v_add_f32_e32 v52, v52, v53
	v_mul_f32_e32 v53, v43, v43
	v_add_f32_e32 v40, v40, v41
	v_mul_f32_e32 v41, v35, v35
	v_fmac_f32_e32 v53, v42, v42
	v_fmac_f32_e32 v41, v34, v34
	v_add_f32_e32 v52, v53, v52
	v_add_f32_e32 v40, v41, v40
	v_cvt_pk_bf16_f32 v47, v42, v43
	v_add_f32_e32 v42, v52, v40
	ds_bpermute_b32 v43, v156, v42
	v_add_u32_e32 v48, 0x90, v146
	v_ashrrev_i32_e32 v49, 31, v48
	v_lshlrev_b64 v[50:51], 11, v[48:49]
	v_lshl_add_u64 v[40:41], s[8:9], 0, v[50:51]
	v_lshl_add_u64 v[50:51], v[144:145], 1, v[40:41]
	v_cvt_pk_bf16_f32 v40, v36, v37
	s_waitcnt lgkmcnt(0)
	v_add_f32_e32 v36, v42, v43
	ds_bpermute_b32 v37, v155, v36
	v_cvt_pk_bf16_f32 v41, v38, v39
	v_cvt_pk_bf16_f32 v42, v32, v33
	v_cvt_pk_bf16_f32 v43, v34, v35
	global_store_dwordx4 v[50:51], v[44:47], off sc1
	global_store_dwordx4 v[50:51], v[40:43], off offset:256 sc1
	s_and_saveexec_b64 s[30:31], s[4:5]
	s_cbranch_execz .LBB0_741
	v_lshlrev_b64 v[32:33], 6, v[48:49]
	v_lshl_add_u64 v[32:33], s[10:11], 0, v[32:33]
	v_lshl_add_u64 v[32:33], s[28:29], 2, v[32:33]
	s_lshl_b32 s12, s43, 2
	s_waitcnt lgkmcnt(0)
	v_add_f32_e32 v34, v36, v37
	v_lshl_add_u64 v[32:33], v[32:33], 0, s[12:13]
	global_store_dword v[32:33], v34, off
.LBB0_741:
	s_or_b64 exec, exec, s[30:31]
	v_mul_f32_e32 v36, v29, v29
	s_waitcnt lgkmcnt(0)
	v_mul_f32_e32 v37, v31, v31
	v_fmac_f32_e32 v36, v28, v28
	v_fmac_f32_e32 v37, v30, v30
	v_add_f32_e32 v36, v36, v37
	v_mul_f32_e32 v37, v25, v25
	v_fmac_f32_e32 v37, v24, v24
	v_cvt_pk_bf16_f32 v28, v28, v29
	v_cvt_pk_bf16_f32 v29, v30, v31
	v_cvt_pk_bf16_f32 v30, v24, v25
	v_mul_f32_e32 v24, v21, v21
	v_mul_f32_e32 v25, v23, v23
	v_fmac_f32_e32 v24, v20, v20
	v_fmac_f32_e32 v25, v22, v22
	v_add_f32_e32 v24, v24, v25
	v_mul_f32_e32 v25, v17, v17
	v_fmac_f32_e32 v25, v16, v16
	v_add_f32_e32 v36, v36, v37
	v_mul_f32_e32 v37, v27, v27
	v_add_f32_e32 v24, v24, v25
	v_mul_f32_e32 v25, v19, v19
	v_fmac_f32_e32 v37, v26, v26
	v_fmac_f32_e32 v25, v18, v18
	v_add_f32_e32 v36, v37, v36
	v_add_f32_e32 v24, v25, v24
	v_cvt_pk_bf16_f32 v31, v26, v27
	v_add_f32_e32 v26, v36, v24
	ds_bpermute_b32 v27, v156, v26
	v_add_u32_e32 v32, 0xa0, v146
	v_ashrrev_i32_e32 v33, 31, v32
	v_lshlrev_b64 v[34:35], 11, v[32:33]
	v_lshl_add_u64 v[24:25], s[8:9], 0, v[34:35]
	v_lshl_add_u64 v[34:35], v[144:145], 1, v[24:25]
	v_cvt_pk_bf16_f32 v24, v20, v21
	s_waitcnt lgkmcnt(0)
	v_add_f32_e32 v20, v26, v27
	ds_bpermute_b32 v21, v155, v20
	v_cvt_pk_bf16_f32 v25, v22, v23
	v_cvt_pk_bf16_f32 v26, v16, v17
	v_cvt_pk_bf16_f32 v27, v18, v19
	global_store_dwordx4 v[34:35], v[28:31], off sc1
	global_store_dwordx4 v[34:35], v[24:27], off offset:256 sc1
	s_and_saveexec_b64 s[30:31], s[4:5]
	s_cbranch_execz .LBB0_743
	v_lshlrev_b64 v[16:17], 6, v[32:33]
	v_lshl_add_u64 v[16:17], s[10:11], 0, v[16:17]
	v_lshl_add_u64 v[16:17], s[28:29], 2, v[16:17]
	s_lshl_b32 s12, s43, 2
	s_waitcnt lgkmcnt(0)
	v_add_f32_e32 v18, v20, v21
	v_lshl_add_u64 v[16:17], v[16:17], 0, s[12:13]
	global_store_dword v[16:17], v18, off
.LBB0_743:
	s_or_b64 exec, exec, s[30:31]
	v_mul_f32_e32 v20, v13, v13
	s_waitcnt lgkmcnt(0)
	v_mul_f32_e32 v21, v15, v15
	v_fmac_f32_e32 v20, v12, v12
	v_fmac_f32_e32 v21, v14, v14
	v_add_f32_e32 v20, v20, v21
	v_mul_f32_e32 v21, v9, v9
	v_fmac_f32_e32 v21, v8, v8
	v_cvt_pk_bf16_f32 v12, v12, v13
	v_cvt_pk_bf16_f32 v13, v14, v15
	v_cvt_pk_bf16_f32 v14, v8, v9
	v_mul_f32_e32 v8, v5, v5
	v_mul_f32_e32 v9, v7, v7
	v_fmac_f32_e32 v8, v4, v4
	v_fmac_f32_e32 v9, v6, v6
	v_add_f32_e32 v8, v8, v9
	v_mul_f32_e32 v9, v1, v1
	v_fmac_f32_e32 v9, v0, v0
	v_add_f32_e32 v20, v20, v21
	v_mul_f32_e32 v21, v11, v11
	v_add_f32_e32 v8, v8, v9
	v_mul_f32_e32 v9, v3, v3
	v_fmac_f32_e32 v21, v10, v10
	v_fmac_f32_e32 v9, v2, v2
	v_add_f32_e32 v20, v21, v20
	v_add_f32_e32 v8, v9, v8
	v_cvt_pk_bf16_f32 v15, v10, v11
	v_add_f32_e32 v10, v20, v8
	ds_bpermute_b32 v11, v156, v10
	v_add_u32_e32 v16, 0xb0, v146
	v_ashrrev_i32_e32 v17, 31, v16
	v_lshlrev_b64 v[18:19], 11, v[16:17]
	v_lshl_add_u64 v[8:9], s[8:9], 0, v[18:19]
	v_lshl_add_u64 v[18:19], v[144:145], 1, v[8:9]
	v_cvt_pk_bf16_f32 v8, v4, v5
	s_waitcnt lgkmcnt(0)
	v_add_f32_e32 v4, v10, v11
	ds_bpermute_b32 v5, v155, v4
	v_cvt_pk_bf16_f32 v9, v6, v7
	v_cvt_pk_bf16_f32 v10, v0, v1
	v_cvt_pk_bf16_f32 v11, v2, v3
	global_store_dwordx4 v[18:19], v[12:15], off sc1
	global_store_dwordx4 v[18:19], v[8:11], off offset:256 sc1
	s_and_saveexec_b64 s[30:31], s[4:5]
	s_cbranch_execz .LBB0_745
	v_lshlrev_b64 v[0:1], 6, v[16:17]
	v_lshl_add_u64 v[0:1], s[10:11], 0, v[0:1]
	v_lshl_add_u64 v[0:1], s[28:29], 2, v[0:1]
	s_lshl_b32 s12, s43, 2
	s_waitcnt lgkmcnt(0)
	v_add_f32_e32 v2, v4, v5
	v_lshl_add_u64 v[0:1], v[0:1], 0, s[12:13]
	global_store_dword v[0:1], v2, off

.LBB0_957:
	v_mul_f32_e32 v157, v125, v125
	v_mul_f32_e32 v160, v127, v127
	v_fmac_f32_e32 v157, v124, v124
	v_fmac_f32_e32 v160, v126, v126
	v_add_f32_e32 v157, v157, v160
	v_mul_f32_e32 v160, v121, v121
	v_fmac_f32_e32 v160, v120, v120
	v_cvt_pk_bf16_f32 v124, v124, v125
	v_cvt_pk_bf16_f32 v125, v126, v127
	v_cvt_pk_bf16_f32 v126, v120, v121
	v_mul_f32_e32 v120, v117, v117
	v_mul_f32_e32 v121, v119, v119
	v_fmac_f32_e32 v120, v116, v116
	v_fmac_f32_e32 v121, v118, v118
	v_add_f32_e32 v120, v120, v121
	v_mul_f32_e32 v121, v113, v113
	v_and_b32_e32 v155, 64, v154
	v_fmac_f32_e32 v121, v112, v112
	v_xor_b32_e32 v147, 16, v154
	v_add_u32_e32 v155, 64, v155
	v_add_f32_e32 v157, v157, v160
	v_mul_f32_e32 v160, v123, v123
	v_add_f32_e32 v120, v120, v121
	v_mul_f32_e32 v121, v115, v115
	v_cmp_lt_i32_e32 vcc, v147, v155
	v_fmac_f32_e32 v160, v122, v122
	v_fmac_f32_e32 v121, v114, v114
	v_cndmask_b32_e32 v147, v154, v147, vcc
	v_add_f32_e32 v157, v160, v157
	v_add_f32_e32 v120, v121, v120
	v_lshlrev_b32_e32 v156, 2, v147
	v_xor_b32_e32 v147, 32, v154
	v_cvt_pk_bf16_f32 v127, v122, v123
	v_add_f32_e32 v122, v157, v120
	v_cmp_lt_i32_e32 vcc, v147, v155
	ds_bpermute_b32 v123, v156, v122
	v_lshl_add_u32 v146, s30, 8, v148
	v_cndmask_b32_e32 v147, v154, v147, vcc
	v_lshlrev_b32_e32 v155, 2, v147
	v_ashrrev_i32_e32 v147, 31, v146
	v_lshl_or_b32 v144, s14, 8, v150
	v_lshlrev_b64 v[158:159], 11, v[146:147]
	v_ashrrev_i32_e32 v145, 31, v144
	v_lshl_add_u64 v[120:121], s[66:67], 0, v[158:159]
	v_lshl_add_u64 v[158:159], v[144:145], 1, v[120:121]
	v_cvt_pk_bf16_f32 v120, v116, v117
	s_waitcnt lgkmcnt(0)
	v_add_f32_e32 v116, v122, v123
	ds_bpermute_b32 v117, v155, v116
	s_lshl_b32 s30, s14, 2
	s_ashr_i32 s31, s30, 31
	v_cvt_pk_bf16_f32 v121, v118, v119
	v_cvt_pk_bf16_f32 v122, v112, v113
	v_cvt_pk_bf16_f32 v123, v114, v115
	global_store_dwordx4 v[158:159], v[124:127], off sc1
	global_store_dwordx4 v[158:159], v[120:123], off offset:256 sc1
	s_and_saveexec_b64 s[34:35], s[4:5]
	s_cbranch_execz .LBB0_959
	v_lshlrev_b64 v[112:113], 6, v[146:147]
	v_lshl_add_u64 v[112:113], s[0:1], 0, v[112:113]
	v_lshl_add_u64 v[112:113], s[30:31], 2, v[112:113]
	s_lshl_b32 s14, s45, 2
	s_waitcnt lgkmcnt(0)
	v_add_f32_e32 v114, v116, v117
	v_lshl_add_u64 v[112:113], v[112:113], 0, s[14:15]
	global_store_dword v[112:113], v114, off
.LBB0_959:
	s_or_b64 exec, exec, s[34:35]
	v_mul_f32_e32 v116, v109, v109
	s_waitcnt lgkmcnt(0)
	v_mul_f32_e32 v117, v111, v111
	v_fmac_f32_e32 v116, v108, v108
	v_fmac_f32_e32 v117, v110, v110
	v_add_f32_e32 v116, v116, v117
	v_mul_f32_e32 v117, v105, v105
	v_fmac_f32_e32 v117, v104, v104
	v_cvt_pk_bf16_f32 v108, v108, v109
	v_cvt_pk_bf16_f32 v109, v110, v111
	v_cvt_pk_bf16_f32 v110, v104, v105
	v_mul_f32_e32 v104, v101, v101
	v_mul_f32_e32 v105, v103, v103
	v_fmac_f32_e32 v104, v100, v100
	v_fmac_f32_e32 v105, v102, v102
	v_add_f32_e32 v104, v104, v105
	v_mul_f32_e32 v105, v97, v97
	v_fmac_f32_e32 v105, v96, v96
	v_add_f32_e32 v116, v116, v117
	v_mul_f32_e32 v117, v107, v107
	v_add_f32_e32 v104, v104, v105
	v_mul_f32_e32 v105, v99, v99
	v_fmac_f32_e32 v117, v106, v106
	v_fmac_f32_e32 v105, v98, v98
	v_add_f32_e32 v116, v117, v116
	v_add_f32_e32 v104, v105, v104
	v_cvt_pk_bf16_f32 v111, v106, v107
	v_add_f32_e32 v106, v116, v104
	ds_bpermute_b32 v107, v156, v106
	v_or_b32_e32 v112, 16, v146
	v_ashrrev_i32_e32 v113, 31, v112
	v_lshlrev_b64 v[114:115], 11, v[112:113]
	v_lshl_add_u64 v[104:105], s[66:67], 0, v[114:115]
	v_lshl_add_u64 v[114:115], v[144:145], 1, v[104:105]
	v_cvt_pk_bf16_f32 v104, v100, v101
	s_waitcnt lgkmcnt(0)
	v_add_f32_e32 v100, v106, v107
	ds_bpermute_b32 v101, v155, v100
	v_cvt_pk_bf16_f32 v105, v102, v103
	v_cvt_pk_bf16_f32 v106, v96, v97
	v_cvt_pk_bf16_f32 v107, v98, v99
	global_store_dwordx4 v[114:115], v[108:111], off sc1
	global_store_dwordx4 v[114:115], v[104:107], off offset:256 sc1
	s_and_saveexec_b64 s[34:35], s[4:5]
	s_cbranch_execz .LBB0_961
	v_lshlrev_b64 v[96:97], 6, v[112:113]
	v_lshl_add_u64 v[96:97], s[0:1], 0, v[96:97]
	v_lshl_add_u64 v[96:97], s[30:31], 2, v[96:97]
	s_lshl_b32 s14, s45, 2
	s_waitcnt lgkmcnt(0)
	v_add_f32_e32 v98, v100, v101
	v_lshl_add_u64 v[96:97], v[96:97], 0, s[14:15]
	global_store_dword v[96:97], v98, off
.LBB0_961:
	s_or_b64 exec, exec, s[34:35]
	v_mul_f32_e32 v100, v93, v93
	s_waitcnt lgkmcnt(0)
	v_mul_f32_e32 v101, v95, v95
	v_fmac_f32_e32 v100, v92, v92
	v_fmac_f32_e32 v101, v94, v94
	v_add_f32_e32 v100, v100, v101
	v_mul_f32_e32 v101, v89, v89
	v_fmac_f32_e32 v101, v88, v88
	v_cvt_pk_bf16_f32 v92, v92, v93
	v_cvt_pk_bf16_f32 v93, v94, v95
	v_cvt_pk_bf16_f32 v94, v88, v89
	v_mul_f32_e32 v88, v85, v85
	v_mul_f32_e32 v89, v87, v87
	v_fmac_f32_e32 v88, v84, v84
	v_fmac_f32_e32 v89, v86, v86
	v_add_f32_e32 v88, v88, v89
	v_mul_f32_e32 v89, v81, v81
	v_fmac_f32_e32 v89, v80, v80
	v_add_f32_e32 v100, v100, v101
	v_mul_f32_e32 v101, v91, v91
	v_add_f32_e32 v88, v88, v89
	v_mul_f32_e32 v89, v83, v83
	v_fmac_f32_e32 v101, v90, v90
	v_fmac_f32_e32 v89, v82, v82
	v_add_f32_e32 v100, v101, v100
	v_add_f32_e32 v88, v89, v88
	v_cvt_pk_bf16_f32 v95, v90, v91
	v_add_f32_e32 v90, v100, v88
	ds_bpermute_b32 v91, v156, v90
	v_or_b32_e32 v96, 32, v146
	v_ashrrev_i32_e32 v97, 31, v96
	v_lshlrev_b64 v[98:99], 11, v[96:97]
	v_lshl_add_u64 v[88:89], s[66:67], 0, v[98:99]
	v_lshl_add_u64 v[98:99], v[144:145], 1, v[88:89]
	v_cvt_pk_bf16_f32 v88, v84, v85
	s_waitcnt lgkmcnt(0)
	v_add_f32_e32 v84, v90, v91
	ds_bpermute_b32 v85, v155, v84
	v_cvt_pk_bf16_f32 v89, v86, v87
	v_cvt_pk_bf16_f32 v90, v80, v81
	v_cvt_pk_bf16_f32 v91, v82, v83
	global_store_dwordx4 v[98:99], v[92:95], off sc1
	global_store_dwordx4 v[98:99], v[88:91], off offset:256 sc1
	s_and_saveexec_b64 s[34:35], s[4:5]
	s_cbranch_execz .LBB0_963
	v_lshlrev_b64 v[80:81], 6, v[96:97]
	v_lshl_add_u64 v[80:81], s[0:1], 0, v[80:81]
	v_lshl_add_u64 v[80:81], s[30:31], 2, v[80:81]
	s_lshl_b32 s14, s45, 2
	s_waitcnt lgkmcnt(0)
	v_add_f32_e32 v82, v84, v85
	v_lshl_add_u64 v[80:81], v[80:81], 0, s[14:15]
	global_store_dword v[80:81], v82, off
.LBB0_963:
	s_or_b64 exec, exec, s[34:35]
	v_mul_f32_e32 v84, v77, v77
	s_waitcnt lgkmcnt(0)
	v_mul_f32_e32 v85, v79, v79
	v_fmac_f32_e32 v84, v76, v76
	v_fmac_f32_e32 v85, v78, v78
	v_add_f32_e32 v84, v84, v85
	v_mul_f32_e32 v85, v73, v73
	v_fmac_f32_e32 v85, v72, v72
	v_cvt_pk_bf16_f32 v76, v76, v77
	v_cvt_pk_bf16_f32 v77, v78, v79
	v_cvt_pk_bf16_f32 v78, v72, v73
	v_mul_f32_e32 v72, v69, v69
	v_mul_f32_e32 v73, v71, v71
	v_fmac_f32_e32 v72, v68, v68
	v_fmac_f32_e32 v73, v70, v70
	v_add_f32_e32 v72, v72, v73
	v_mul_f32_e32 v73, v65, v65
	v_fmac_f32_e32 v73, v64, v64
	v_add_f32_e32 v84, v84, v85
	v_mul_f32_e32 v85, v75, v75
	v_add_f32_e32 v72, v72, v73
	v_mul_f32_e32 v73, v67, v67
	v_fmac_f32_e32 v85, v74, v74
	v_fmac_f32_e32 v73, v66, v66
	v_add_f32_e32 v84, v85, v84
	v_add_f32_e32 v72, v73, v72
	v_cvt_pk_bf16_f32 v79, v74, v75
	v_add_f32_e32 v74, v84, v72
	ds_bpermute_b32 v75, v156, v74
	v_or_b32_e32 v80, 48, v146
	v_ashrrev_i32_e32 v81, 31, v80
	v_lshlrev_b64 v[82:83], 11, v[80:81]
	v_lshl_add_u64 v[72:73], s[66:67], 0, v[82:83]
	v_lshl_add_u64 v[82:83], v[144:145], 1, v[72:73]
	v_cvt_pk_bf16_f32 v72, v68, v69
	s_waitcnt lgkmcnt(0)
	v_add_f32_e32 v68, v74, v75
	ds_bpermute_b32 v69, v155, v68
	v_cvt_pk_bf16_f32 v73, v70, v71
	v_cvt_pk_bf16_f32 v74, v64, v65
	v_cvt_pk_bf16_f32 v75, v66, v67
	global_store_dwordx4 v[82:83], v[76:79], off sc1
	global_store_dwordx4 v[82:83], v[72:75], off offset:256 sc1
	s_and_saveexec_b64 s[34:35], s[4:5]
	s_cbranch_execz .LBB0_965
	v_lshlrev_b64 v[64:65], 6, v[80:81]
	v_lshl_add_u64 v[64:65], s[0:1], 0, v[64:65]
	v_lshl_add_u64 v[64:65], s[30:31], 2, v[64:65]
	s_lshl_b32 s14, s45, 2
	s_waitcnt lgkmcnt(0)
	v_add_f32_e32 v66, v68, v69
	v_lshl_add_u64 v[64:65], v[64:65], 0, s[14:15]
	global_store_dword v[64:65], v66, off
.LBB0_965:
	s_or_b64 exec, exec, s[34:35]
	v_mul_f32_e32 v68, v61, v61
	s_waitcnt lgkmcnt(0)
	v_mul_f32_e32 v69, v63, v63
	v_fmac_f32_e32 v68, v60, v60
	v_fmac_f32_e32 v69, v62, v62
	v_add_f32_e32 v68, v68, v69
	v_mul_f32_e32 v69, v57, v57
	v_fmac_f32_e32 v69, v56, v56
	v_cvt_pk_bf16_f32 v60, v60, v61
	v_cvt_pk_bf16_f32 v61, v62, v63
	v_cvt_pk_bf16_f32 v62, v56, v57
	v_mul_f32_e32 v56, v53, v53
	v_mul_f32_e32 v57, v55, v55
	v_fmac_f32_e32 v56, v52, v52
	v_fmac_f32_e32 v57, v54, v54
	v_add_f32_e32 v56, v56, v57
	v_mul_f32_e32 v57, v49, v49
	v_fmac_f32_e32 v57, v48, v48
	v_add_f32_e32 v68, v68, v69
	v_mul_f32_e32 v69, v59, v59
	v_add_f32_e32 v56, v56, v57
	v_mul_f32_e32 v57, v51, v51
	v_fmac_f32_e32 v69, v58, v58
	v_fmac_f32_e32 v57, v50, v50
	v_add_f32_e32 v68, v69, v68
	v_add_f32_e32 v56, v57, v56
	v_cvt_pk_bf16_f32 v63, v58, v59
	v_add_f32_e32 v58, v68, v56
	ds_bpermute_b32 v59, v156, v58
	v_add_u32_e32 v64, 0x80, v146
	v_ashrrev_i32_e32 v65, 31, v64
	v_lshlrev_b64 v[66:67], 11, v[64:65]
	v_lshl_add_u64 v[56:57], s[66:67], 0, v[66:67]
	v_lshl_add_u64 v[66:67], v[144:145], 1, v[56:57]
	v_cvt_pk_bf16_f32 v56, v52, v53
	s_waitcnt lgkmcnt(0)
	v_add_f32_e32 v52, v58, v59
	ds_bpermute_b32 v53, v155, v52
	v_cvt_pk_bf16_f32 v57, v54, v55
	v_cvt_pk_bf16_f32 v58, v48, v49
	v_cvt_pk_bf16_f32 v59, v50, v51
	global_store_dwordx4 v[66:67], v[60:63], off sc1
	global_store_dwordx4 v[66:67], v[56:59], off offset:256 sc1
	s_and_saveexec_b64 s[34:35], s[4:5]
	s_cbranch_execz .LBB0_967
	v_lshlrev_b64 v[48:49], 6, v[64:65]
	v_lshl_add_u64 v[48:49], s[0:1], 0, v[48:49]
	v_lshl_add_u64 v[48:49], s[30:31], 2, v[48:49]
	s_lshl_b32 s14, s45, 2
	s_waitcnt lgkmcnt(0)
	v_add_f32_e32 v50, v52, v53
	v_lshl_add_u64 v[48:49], v[48:49], 0, s[14:15]
	global_store_dword v[48:49], v50, off
.LBB0_967:
	s_or_b64 exec, exec, s[34:35]
	v_mul_f32_e32 v52, v45, v45
	s_waitcnt lgkmcnt(0)
	v_mul_f32_e32 v53, v47, v47
	v_fmac_f32_e32 v52, v44, v44
	v_fmac_f32_e32 v53, v46, v46
	v_add_f32_e32 v52, v52, v53
	v_mul_f32_e32 v53, v41, v41
	v_fmac_f32_e32 v53, v40, v40
	v_cvt_pk_bf16_f32 v44, v44, v45
	v_cvt_pk_bf16_f32 v45, v46, v47
	v_cvt_pk_bf16_f32 v46, v40, v41
	v_mul_f32_e32 v40, v37, v37
	v_mul_f32_e32 v41, v39, v39
	v_fmac_f32_e32 v40, v36, v36
	v_fmac_f32_e32 v41, v38, v38
	v_add_f32_e32 v40, v40, v41
	v_mul_f32_e32 v41, v33, v33
	v_fmac_f32_e32 v41, v32, v32
	v_add_f32_e32 v52, v52, v53
	v_mul_f32_e32 v53, v43, v43
	v_add_f32_e32 v40, v40, v41
	v_mul_f32_e32 v41, v35, v35
	v_fmac_f32_e32 v53, v42, v42
	v_fmac_f32_e32 v41, v34, v34
	v_add_f32_e32 v52, v53, v52
	v_add_f32_e32 v40, v41, v40
	v_cvt_pk_bf16_f32 v47, v42, v43
	v_add_f32_e32 v42, v52, v40
	ds_bpermute_b32 v43, v156, v42
	v_add_u32_e32 v48, 0x90, v146
	v_ashrrev_i32_e32 v49, 31, v48
	v_lshlrev_b64 v[50:51], 11, v[48:49]
	v_lshl_add_u64 v[40:41], s[66:67], 0, v[50:51]
	v_lshl_add_u64 v[50:51], v[144:145], 1, v[40:41]
	v_cvt_pk_bf16_f32 v40, v36, v37
	s_waitcnt lgkmcnt(0)
	v_add_f32_e32 v36, v42, v43
	ds_bpermute_b32 v37, v155, v36
	v_cvt_pk_bf16_f32 v41, v38, v39
	v_cvt_pk_bf16_f32 v42, v32, v33
	v_cvt_pk_bf16_f32 v43, v34, v35
	global_store_dwordx4 v[50:51], v[44:47], off sc1
	global_store_dwordx4 v[50:51], v[40:43], off offset:256 sc1
	s_and_saveexec_b64 s[34:35], s[4:5]
	s_cbranch_execz .LBB0_969
	v_lshlrev_b64 v[32:33], 6, v[48:49]
	v_lshl_add_u64 v[32:33], s[0:1], 0, v[32:33]
	v_lshl_add_u64 v[32:33], s[30:31], 2, v[32:33]
	s_lshl_b32 s14, s45, 2
	s_waitcnt lgkmcnt(0)
	v_add_f32_e32 v34, v36, v37
	v_lshl_add_u64 v[32:33], v[32:33], 0, s[14:15]
	global_store_dword v[32:33], v34, off
.LBB0_969:
	s_or_b64 exec, exec, s[34:35]
	v_mul_f32_e32 v36, v29, v29
	s_waitcnt lgkmcnt(0)
	v_mul_f32_e32 v37, v31, v31
	v_fmac_f32_e32 v36, v28, v28
	v_fmac_f32_e32 v37, v30, v30
	v_add_f32_e32 v36, v36, v37
	v_mul_f32_e32 v37, v25, v25
	v_fmac_f32_e32 v37, v24, v24
	v_cvt_pk_bf16_f32 v28, v28, v29
	v_cvt_pk_bf16_f32 v29, v30, v31
	v_cvt_pk_bf16_f32 v30, v24, v25
	v_mul_f32_e32 v24, v21, v21
	v_mul_f32_e32 v25, v23, v23
	v_fmac_f32_e32 v24, v20, v20
	v_fmac_f32_e32 v25, v22, v22
	v_add_f32_e32 v24, v24, v25
	v_mul_f32_e32 v25, v17, v17
	v_fmac_f32_e32 v25, v16, v16
	v_add_f32_e32 v36, v36, v37
	v_mul_f32_e32 v37, v27, v27
	v_add_f32_e32 v24, v24, v25
	v_mul_f32_e32 v25, v19, v19
	v_fmac_f32_e32 v37, v26, v26
	v_fmac_f32_e32 v25, v18, v18
	v_add_f32_e32 v36, v37, v36
	v_add_f32_e32 v24, v25, v24
	v_cvt_pk_bf16_f32 v31, v26, v27
	v_add_f32_e32 v26, v36, v24
	ds_bpermute_b32 v27, v156, v26
	v_add_u32_e32 v32, 0xa0, v146
	v_ashrrev_i32_e32 v33, 31, v32
	v_lshlrev_b64 v[34:35], 11, v[32:33]
	v_lshl_add_u64 v[24:25], s[66:67], 0, v[34:35]
	v_lshl_add_u64 v[34:35], v[144:145], 1, v[24:25]
	v_cvt_pk_bf16_f32 v24, v20, v21
	s_waitcnt lgkmcnt(0)
	v_add_f32_e32 v20, v26, v27
	ds_bpermute_b32 v21, v155, v20
	v_cvt_pk_bf16_f32 v25, v22, v23
	v_cvt_pk_bf16_f32 v26, v16, v17
	v_cvt_pk_bf16_f32 v27, v18, v19
	global_store_dwordx4 v[34:35], v[28:31], off sc1
	global_store_dwordx4 v[34:35], v[24:27], off offset:256 sc1
	s_and_saveexec_b64 s[34:35], s[4:5]
	s_cbranch_execz .LBB0_971
	v_lshlrev_b64 v[16:17], 6, v[32:33]
	v_lshl_add_u64 v[16:17], s[0:1], 0, v[16:17]
	v_lshl_add_u64 v[16:17], s[30:31], 2, v[16:17]
	s_lshl_b32 s14, s45, 2
	s_waitcnt lgkmcnt(0)
	v_add_f32_e32 v18, v20, v21
	v_lshl_add_u64 v[16:17], v[16:17], 0, s[14:15]
	global_store_dword v[16:17], v18, off
.LBB0_971:
	s_or_b64 exec, exec, s[34:35]
	v_mul_f32_e32 v20, v13, v13
	s_waitcnt lgkmcnt(0)
	v_mul_f32_e32 v21, v15, v15
	v_fmac_f32_e32 v20, v12, v12
	v_fmac_f32_e32 v21, v14, v14
	v_add_f32_e32 v20, v20, v21
	v_mul_f32_e32 v21, v9, v9
	v_fmac_f32_e32 v21, v8, v8
	v_cvt_pk_bf16_f32 v12, v12, v13
	v_cvt_pk_bf16_f32 v13, v14, v15
	v_cvt_pk_bf16_f32 v14, v8, v9
	v_mul_f32_e32 v8, v5, v5
	v_mul_f32_e32 v9, v7, v7
	v_fmac_f32_e32 v8, v4, v4
	v_fmac_f32_e32 v9, v6, v6
	v_add_f32_e32 v8, v8, v9
	v_mul_f32_e32 v9, v1, v1
	v_fmac_f32_e32 v9, v0, v0
	v_add_f32_e32 v20, v20, v21
	v_mul_f32_e32 v21, v11, v11
	v_add_f32_e32 v8, v8, v9
	v_mul_f32_e32 v9, v3, v3
	v_fmac_f32_e32 v21, v10, v10
	v_fmac_f32_e32 v9, v2, v2
	v_add_f32_e32 v20, v21, v20
	v_add_f32_e32 v8, v9, v8
	v_cvt_pk_bf16_f32 v15, v10, v11
	v_add_f32_e32 v10, v20, v8
	ds_bpermute_b32 v11, v156, v10
	v_add_u32_e32 v16, 0xb0, v146
	v_ashrrev_i32_e32 v17, 31, v16
	v_lshlrev_b64 v[18:19], 11, v[16:17]
	v_lshl_add_u64 v[8:9], s[66:67], 0, v[18:19]
	v_lshl_add_u64 v[18:19], v[144:145], 1, v[8:9]
	v_cvt_pk_bf16_f32 v8, v4, v5
	s_waitcnt lgkmcnt(0)
	v_add_f32_e32 v4, v10, v11
	ds_bpermute_b32 v5, v155, v4
	v_cvt_pk_bf16_f32 v9, v6, v7
	v_cvt_pk_bf16_f32 v10, v0, v1
	v_cvt_pk_bf16_f32 v11, v2, v3
	global_store_dwordx4 v[18:19], v[12:15], off sc1
	global_store_dwordx4 v[18:19], v[8:11], off offset:256 sc1
	s_and_saveexec_b64 s[34:35], s[4:5]
	s_cbranch_execz .LBB0_973
	v_lshlrev_b64 v[0:1], 6, v[16:17]
	v_lshl_add_u64 v[0:1], s[0:1], 0, v[0:1]
	v_lshl_add_u64 v[0:1], s[30:31], 2, v[0:1]
	s_lshl_b32 s14, s45, 2
	s_waitcnt lgkmcnt(0)
	v_add_f32_e32 v2, v4, v5
	v_lshl_add_u64 v[0:1], v[0:1], 0, s[14:15]
	global_store_dword v[0:1], v2, off
